# seldesc: selected branch visits union list in descending order; first pair (qblk,qblk-1) prefetched before selection; prologue has no exposed global loads
# baseline (speedup 1.0000x reference)
.LBB0_1029:
	s_or_b64 exec, exec, s[0:1]
	s_waitcnt lgkmcnt(0)
	s_barrier
	ds_read2st64_b32 v[0:1], v173 offset1:1
	v_add_u32_e32 v7, 0xf0, v174
	ds_read_b64 v[2:3], v161
	ds_read_b64 v[8:9], v162
	ds_read_b64 v[10:11], v163
	ds_read_b64 v[12:13], v164
	ds_read2st64_b32 v[14:15], v174 offset1:1
	ds_read2st64_b32 v[16:17], v174 offset0:33 offset1:34
	ds_read2st64_b32 v[18:19], v174 offset0:66 offset1:67
	ds_read2st64_b32 v[20:21], v174 offset0:99 offset1:100
	ds_read2st64_b32 v[22:23], v7 offset0:30 offset1:31
	ds_read2st64_b32 v[24:25], v7 offset0:63 offset1:64
	ds_read2st64_b32 v[26:27], v7 offset0:96 offset1:97
	ds_read2st64_b32 v[28:29], v7 offset0:129 offset1:130
	ds_read_b64 v[30:31], v165
	ds_read_b64 v[32:33], v166
	ds_read_b64 v[34:35], v167
	ds_read_b64 v[36:37], v168
	ds_read2st64_b32 v[38:39], v7 offset0:162 offset1:163
	ds_read2st64_b32 v[40:41], v7 offset0:195 offset1:196
	ds_read2st64_b32 v[42:43], v7 offset0:228 offset1:229
	ds_read2st64_b32 v[44:45], v174 offset0:132 offset1:133
	ds_read2st64_b32 v[46:47], v174 offset0:165 offset1:166
	ds_read2st64_b32 v[80:81], v174 offset0:198 offset1:199
	ds_read2st64_b32 v[82:83], v174 offset0:231 offset1:232
	s_ashr_i32 s30, s75, 2
	s_add_i32 s31, s30, -1
	s_max_i32 s31, s31, 0
	s_lshl_b32 s98, s40, 25
	s_add_u32 s98, s36, s98
	s_addc_u32 s99, s37, 0
	s_lshl_b32 s20, s29, 7
	s_add_u32 s98, s98, s20
	s_addc_u32 s99, s99, 0
	s_lshl_b32 s20, s47, 20
	s_add_u32 s100, s55, s20
	s_addc_u32 s101, s56, 0
	v_mov_b32_e32 v198, v138
	v_mov_b32_e32 v199, 0
	v_mov_b32_e32 v200, v140
	v_mov_b32_e32 v201, 0
	s_lshl_b32 s22, s30, 18
	s_add_u32 s22, s98, s22
	s_addc_u32 s23, s99, 0
	s_lshl_b32 s24, s30, 7
	s_add_u32 s24, s100, s24
	s_addc_u32 s25, s101, 0
	v_lshl_add_u64 v[194:195], s[22:23], 0, v[198:199]
	v_lshl_add_u64 v[196:197], s[24:25], 0, v[200:201]
	v_lshl_add_u64 v[194:195], v[194:195], 0, v[122:123]
	v_lshl_add_u64 v[196:197], v[196:197], 0, v[122:123]
	global_load_dwordx4 v[240:243], v[194:195], off offset:2560
	global_load_dwordx4 v[244:247], v[196:197], off
	s_lshl_b32 s22, s31, 18
	s_add_u32 s22, s98, s22
	s_addc_u32 s23, s99, 0
	s_lshl_b32 s24, s31, 7
	s_add_u32 s24, s100, s24
	s_addc_u32 s25, s101, 0
	v_lshl_add_u64 v[194:195], s[22:23], 0, v[198:199]
	v_lshl_add_u64 v[196:197], s[24:25], 0, v[200:201]
	v_lshl_add_u64 v[194:195], v[194:195], 0, v[122:123]
	v_lshl_add_u64 v[196:197], v[196:197], 0, v[122:123]
	global_load_dwordx4 v[248:251], v[194:195], off offset:2560
	global_load_dwordx4 v[252:255], v[196:197], off
	s_ashr_i32 s76, s75, 2
	v_cmp_eq_u32_e64 s[0:1], s76, v128
	s_waitcnt lgkmcnt(14)
	v_mov_b32_e32 v84, v1
	v_mov_b32_e32 v85, v0
	v_pk_fma_f32 v[0:1], v[2:3], v[84:85], 0 op_sel_hi:[0,1,0]
	v_mov_b32_e32 v84, v23
	v_mov_b32_e32 v85, v22
	v_pk_fma_f32 v[0:1], v[8:9], v[84:85], v[0:1] op_sel_hi:[0,1,1]
	s_waitcnt lgkmcnt(13)
	v_mov_b32_e32 v22, v25
	v_mov_b32_e32 v23, v24
	v_pk_fma_f32 v[0:1], v[10:11], v[22:23], v[0:1] op_sel_hi:[0,1,1]
	s_waitcnt lgkmcnt(12)
	v_mov_b32_e32 v22, v27
	v_mov_b32_e32 v23, v26
	v_pk_fma_f32 v[0:1], v[12:13], v[22:23], v[0:1] op_sel_hi:[0,1,1]
	s_waitcnt lgkmcnt(11)
	v_mov_b32_e32 v22, v29
	v_mov_b32_e32 v23, v28
	s_waitcnt lgkmcnt(10)
	v_pk_fma_f32 v[0:1], v[30:31], v[22:23], v[0:1] op_sel_hi:[0,1,1]
	s_waitcnt lgkmcnt(6)
	v_mov_b32_e32 v22, v39
	v_mov_b32_e32 v23, v38
	v_pk_fma_f32 v[0:1], v[32:33], v[22:23], v[0:1] op_sel_hi:[0,1,1]
	s_waitcnt lgkmcnt(5)
	v_mov_b32_e32 v22, v41
	v_mov_b32_e32 v23, v40
	v_pk_fma_f32 v[0:1], v[34:35], v[22:23], v[0:1] op_sel_hi:[0,1,1]
	s_waitcnt lgkmcnt(4)
	v_mov_b32_e32 v22, v43
	v_mov_b32_e32 v23, v42
	v_pk_fma_f32 v[0:1], v[36:37], v[22:23], v[0:1] op_sel_hi:[0,1,1]
	v_mov_b32_e32 v22, v15
	v_mov_b32_e32 v23, v14
	v_pk_fma_f32 v[2:3], v[2:3], v[22:23], 0 op_sel:[1,0,0] op_sel_hi:[1,1,0]
	v_mov_b32_e32 v14, v17
	v_mov_b32_e32 v15, v16
	v_pk_fma_f32 v[2:3], v[8:9], v[14:15], v[2:3] op_sel:[1,0,0]
	v_mov_b32_e32 v8, v19
	v_mov_b32_e32 v9, v18
	v_pk_fma_f32 v[2:3], v[10:11], v[8:9], v[2:3] op_sel:[1,0,0]
	v_mov_b32_e32 v8, v21
	v_mov_b32_e32 v9, v20
	v_pk_fma_f32 v[2:3], v[12:13], v[8:9], v[2:3] op_sel:[1,0,0]
	s_waitcnt lgkmcnt(3)
	v_mov_b32_e32 v8, v45
	v_mov_b32_e32 v9, v44
	v_pk_fma_f32 v[2:3], v[30:31], v[8:9], v[2:3] op_sel:[1,0,0]
	s_waitcnt lgkmcnt(2)
	v_mov_b32_e32 v8, v47
	v_mov_b32_e32 v9, v46
	s_add_i32 s24, s76, 0xffffffbf
	s_add_i32 s22, s76, -1
	v_pk_fma_f32 v[2:3], v[32:33], v[8:9], v[2:3] op_sel:[1,0,0]
	s_waitcnt lgkmcnt(1)
	v_mov_b32_e32 v8, v81
	v_mov_b32_e32 v9, v80
	s_or_b64 s[26:27], s[6:7], s[0:1]
	v_cmp_eq_u32_e64 s[0:1], s76, v156
	v_pk_fma_f32 v[2:3], v[34:35], v[8:9], v[2:3] op_sel:[1,0,0]
	s_waitcnt lgkmcnt(0)
	v_mov_b32_e32 v8, v83
	v_mov_b32_e32 v9, v82
	v_cmp_eq_u32_e64 s[22:23], s22, v127
	v_cmp_eq_u32_e64 s[24:25], s24, v128
	v_pk_fma_f32 v[8:9], v[36:37], v[8:9], v[2:3] op_sel:[1,0,0]
	s_or_b64 s[22:23], s[26:27], s[22:23]
	s_or_b64 s[0:1], s[0:1], s[24:25]
	v_cmp_ge_i32_e64 s[20:21], s76, v128
	v_cmp_ge_i32_e32 vcc, s76, v156
	v_cndmask_b32_e64 v3, v1, v182, s[22:23]
	v_cndmask_b32_e64 v2, v0, v182, s[0:1]
	v_cndmask_b32_e64 v1, v9, v182, s[22:23]
	v_cndmask_b32_e64 v0, v8, v182, s[0:1]
	s_mov_b32 s77, 30
	s_mov_b32 s31, 0
	s_mov_b32 s30, 0
	s_mov_b32 s98, 64
	s_mov_b32 s100, 64

.LBB0_1038:
	s_or_b64 exec, exec, s[0:1]
	s_bcnt1_i32_b32 s0, s21
	s_bcnt1_i32_b32 s1, s22
	s_bcnt1_i32_b32 s21, s23
	s_lshl_b32 s22, s40, 25
	s_add_u32 s22, s36, s22
	s_addc_u32 s23, s37, 0
	s_bcnt1_i32_b32 s20, s20
	s_add_i32 s0, s0, s20
	s_add_i32 s79, s0, s1
	s_add_i32 s79, s79, s21
	s_lshl_b32 s0, s29, 7
	s_add_u32 s24, s22, s0
	v_sub_co_u32_e64 v32, s[0:1], s79, 1
	s_waitcnt lgkmcnt(0)
	s_barrier
	s_addc_u32 s25, s23, 0
	s_lshl_b32 s0, s47, 20
	s_add_u32 s20, s55, s0
	s_addc_u32 s21, s56, 0
	v_add_u32_e32 v8, -2, v32
	v_max_i32_e32 v8, 0, v8
	v_add_u32_e32 v9, -3, v32
	v_max_i32_e32 v9, 0, v9
	v_lshl_add_u32 v8, v8, 2, s72
	v_lshl_add_u32 v9, v9, 2, s72
	ds_read_b32 v8, v8
	ds_read_b32 v9, v9
	s_ashr_i32 s32, s75, 2
	s_add_i32 s97, s32, -1
	s_max_i32 s97, s97, 0
	s_cmp_lt_u32 s79, 2
	s_cselect_b64 vcc, -1, 0
	v_mov_b32_e32 v139, v123
	v_mov_b32_e32 v141, v123
	v_readfirstlane_b32 s80, v32
	v_add_f32_e32 v137, v146, v146
	v_mul_f32_e32 v188, 0x40400000, v146
	v_mul_f32_e32 v189, 0x41800000, v146
	v_mul_f32_e32 v190, 0x42000000, v146
	v_mul_f32_e32 v191, 0x42400000, v146
	v_mul_f32_e32 v192, 0, v146
	s_waitcnt vmcnt(0)
	ds_write_b128 v151, v[240:243]
	ds_write2_b64 v187, v[244:245], v[246:247] offset1:2
	ds_write_b128 v151, v[248:251] offset:10240
	ds_write2_b64 v186, v[252:253], v[254:255] offset1:2
	s_lshl_b32 s98, s47, 20
	s_add_u32 s98, s57, s98
	s_addc_u32 s99, s60, 0
	s_add_i32 s29, s74, 0xfffffe01
	s_andn2_b32 s29, s29, 63
	s_cmp_gt_i32 s75, 31
	s_cselect_b32 s29, s29, 0
	s_sub_i32 s30, s74, s29
	s_ashr_i32 s30, s30, 6
	v_mov_b32_e32 v4, v138
	v_mov_b32_e32 v5, 0
	v_mov_b32_e32 v6, v140
	v_mov_b32_e32 v7, 0
	s_min_i32 s22, s30, 0
	s_lshl_b32 s22, s22, 6
	s_add_i32 s22, s22, s29
	s_ashr_i32 s23, s22, 31
	s_lshl_b64 s[100:101], s[22:23], 12
	s_add_u32 s100, s24, s100
	s_addc_u32 s101, s25, s101
	s_lshl_b64 s[22:23], s[22:23], 1
	s_add_u32 s22, s98, s22
	s_addc_u32 s23, s99, s23
	v_lshl_add_u64 v[0:1], s[100:101], 0, v[4:5]
	v_lshl_add_u64 v[2:3], s[22:23], 0, v[6:7]
	v_lshl_add_u64 v[0:1], v[0:1], 0, v[122:123]
	v_lshl_add_u64 v[2:3], v[2:3], 0, v[122:123]
	global_load_dwordx4 v[240:243], v[0:1], off offset:3072
	global_load_dwordx4 v[244:247], v[2:3], off
	s_min_i32 s22, s30, 1
	s_lshl_b32 s22, s22, 6
	s_add_i32 s22, s22, s29
	s_ashr_i32 s23, s22, 31
	s_lshl_b64 s[100:101], s[22:23], 12
	s_add_u32 s100, s24, s100
	s_addc_u32 s101, s25, s101
	s_lshl_b64 s[22:23], s[22:23], 1
	s_add_u32 s22, s98, s22
	s_addc_u32 s23, s99, s23
	v_lshl_add_u64 v[0:1], s[100:101], 0, v[4:5]
	v_lshl_add_u64 v[2:3], s[22:23], 0, v[6:7]
	v_lshl_add_u64 v[0:1], v[0:1], 0, v[122:123]
	v_lshl_add_u64 v[2:3], v[2:3], 0, v[122:123]
	global_load_dwordx4 v[248:251], v[0:1], off offset:3072
	global_load_dwordx4 v[252:255], v[2:3], off
	s_waitcnt lgkmcnt(4)
	v_readfirstlane_b32 s89, v8
	v_readfirstlane_b32 s91, v9
	s_lshl_b32 s0, s89, 6
	s_ashr_i32 s1, s0, 31
	s_lshl_b64 s[22:23], s[0:1], 12
	s_add_u32 s22, s24, s22
	s_addc_u32 s23, s25, s23
	s_lshl_b64 s[0:1], s[0:1], 1
	s_add_u32 s0, s20, s0
	s_addc_u32 s1, s21, s1
	v_lshl_add_u64 v[0:1], s[22:23], 0, v[138:139]
	v_lshl_add_u64 v[2:3], s[0:1], 0, v[140:141]
	v_lshl_add_u64 v[0:1], v[0:1], 0, v[122:123]
	v_lshl_add_u64 v[2:3], v[2:3], 0, v[122:123]
	global_load_dwordx4 v[20:23], v[0:1], off offset:2560
	global_load_dwordx4 v[16:19], v[2:3], off
	s_lshl_b32 s0, s91, 6
	s_ashr_i32 s1, s0, 31
	s_lshl_b64 s[22:23], s[0:1], 12
	s_add_u32 s22, s24, s22
	s_addc_u32 s23, s25, s23
	s_lshl_b64 s[0:1], s[0:1], 1
	s_add_u32 s0, s20, s0
	s_addc_u32 s1, s21, s1
	v_lshl_add_u64 v[4:5], s[22:23], 0, v[138:139]
	v_lshl_add_u64 v[6:7], s[0:1], 0, v[140:141]
	v_lshl_add_u64 v[4:5], v[4:5], 0, v[122:123]
	v_lshl_add_u64 v[6:7], v[6:7], 0, v[122:123]
	global_load_dwordx4 v[28:31], v[4:5], off offset:2560
	global_load_dwordx4 v[24:27], v[6:7], off
	s_waitcnt lgkmcnt(0)
	s_barrier
	v_lshl_add_u64 v[0:1], s[24:25], 0, v[138:139]
	v_lshl_add_u64 v[120:121], v[0:1], 0, v[122:123]
	s_and_b64 vcc, exec, vcc
	s_cbranch_vccnz .LBB0_1050
	v_lshl_add_u64 v[0:1], s[20:21], 0, v[140:141]
	v_mov_b32_e32 v36, 0
	v_lshl_add_u64 v[148:149], v[0:1], 0, v[122:123]
	v_sub_u32_e32 v139, v144, v124
	v_mov_b32_e32 v32, v123
	v_mov_b32_e32 v33, v123
	v_mov_b32_e32 v34, v123
	v_mov_b32_e32 v35, v123
	s_mov_b32 s83, 5
	s_movk_i32 s81, 0x80
	s_mov_b32 s82, s72
	v_mov_b32_e32 v37, v36
	v_mov_b32_e32 v38, v36
	v_mov_b32_e32 v39, v36
	v_mov_b32_e32 v40, v36
	v_mov_b32_e32 v41, v36
	v_mov_b32_e32 v42, v36
	v_mov_b32_e32 v43, v36
	v_mov_b32_e32 v44, v36
	v_mov_b32_e32 v45, v36
	v_mov_b32_e32 v46, v36
	v_mov_b32_e32 v47, v36
	v_mov_b32_e32 v84, v36
	v_mov_b32_e32 v85, v36
	v_mov_b32_e32 v86, v36
	v_mov_b32_e32 v87, v36

.LBB0_1048:
	s_setprio 0
	s_sub_i32 s0, s80, s83
	s_add_i32 s1, s0, 1
	s_max_i32 s1, s1, 0
	s_max_i32 s0, s0, 0
	s_lshl_b32 s1, s1, 2
	s_add_i32 s1, s1, 0x24900
	v_mov_b32_e32 v33, s1
	ds_read_b32 v33, v33
	s_lshl_b32 s0, s0, 2
	s_add_i32 s0, s0, 0x24900
	v_mov_b32_e32 v34, s0
	ds_read_b32 v34, v34
	s_and_b32 s0, s81, 0x80
	s_mulk_i32 s0, 0xa0
	v_add_u32_e32 v32, s0, v151
	s_waitcnt vmcnt(3)
	ds_write_b128 v32, v[20:23]
	v_add_u32_e32 v20, s0, v152
	s_add_i32 s0, s81, 64
	s_and_b32 s0, s0, 0xc0
	v_add_u32_e32 v20, 0xa000, v20
	s_mulk_i32 s0, 0xa0
	s_waitcnt vmcnt(2)
	ds_write2_b64 v20, v[16:17], v[18:19] offset1:2
	v_add_u32_e32 v16, s0, v151
	s_waitcnt vmcnt(1)
	ds_write_b128 v16, v[28:31]
	v_add_u32_e32 v16, s0, v152
	s_add_i32 s0, s83, -1
	s_cmp_lt_u32 s0, s79
	s_cselect_b32 s0, s0, s80
	s_lshl_b32 s0, s0, 2
	s_add_i32 s22, 0, 0x24900
	v_add_u32_e32 v16, 0xa000, v16
	s_add_i32 s0, s22, s0
	s_waitcnt vmcnt(0)
	ds_write2_b64 v16, v[24:25], v[26:27] offset1:2
	s_waitcnt lgkmcnt(4)
	v_readfirstlane_b32 s98, v33
	v_readfirstlane_b32 s99, v34
	s_addk_i32 s81, 0x80
	s_add_i32 s82, s82, 8
	s_add_i32 s1, s83, -1
	s_cmp_ge_u32 s1, s79
	s_cbranch_scc1 .Lsel_skip_pf
	s_lshl_b32 s0, s98, 6
	s_ashr_i32 s1, s0, 31
	s_lshl_b64 s[20:21], s[0:1], 12
	v_lshl_add_u64 v[18:19], s[0:1], 1, v[148:149]
	v_lshl_add_u64 v[16:17], v[120:121], 0, s[20:21]
	global_load_dwordx4 v[20:23], v[16:17], off offset:2560
	s_nop 0
	global_load_dwordx4 v[16:19], v[18:19], off
	s_lshl_b32 s0, s99, 6
	s_ashr_i32 s1, s0, 31
	s_lshl_b64 s[20:21], s[0:1], 12
	v_lshl_add_u64 v[24:25], v[120:121], 0, s[20:21]
	v_lshl_add_u64 v[26:27], s[0:1], 1, v[148:149]
	global_load_dwordx4 v[28:31], v[24:25], off offset:2560
	s_nop 0
	global_load_dwordx4 v[24:27], v[26:27], off

.LBB0_1052:
	s_waitcnt vmcnt(2)
	s_mov_b32 s21, 0
	s_ashr_i32 s22, s21, 5
	s_cmp_eq_u32 s22, 2
	s_cselect_b32 s0, s77, s78
	s_cmp_eq_u32 s22, 1
	s_cselect_b32 s0, s27, s0
	s_cmp_lt_u32 s21, 32
	s_cselect_b32 s0, s26, s0
	s_lshl_b32 s23, 1, s21
	s_and_b32 s26, s0, s23
	s_mov_b64 s[0:1], -1
	s_cmp_lg_u32 s26, 0
	s_mov_b64 s[26:27], -1
	s_cbranch_scc1 .LBB0_1054
	v_lshl_add_u32 v16, s22, 2, v160
	ds_read_b32 v16, v16
	s_waitcnt lgkmcnt(0)
	v_and_b32_e32 v16, s23, v16
	v_cmp_ne_u32_e32 vcc, 0, v16
	s_orn2_b64 s[26:27], vcc, exec
